# diff-attention tile loops: first two P.V MFMAs of the previous tile issued right after Q.K^T with the row-max/threshold computation in their shadow
# speedup vs baseline: 1.0122x; 1.0005x over previous
.LBB0_293:
	s_waitcnt lgkmcnt(2)
	v_mfma_f32_32x32x16_bf16 v[114:129], v[182:185], v[190:193], v[114:129]
	v_add_u32_e32 v195, s3, v230
	ds_read_b64_tr_b16 v[190:191], v195 offset:49152
	ds_read_b64_tr_b16 v[192:193], v195 offset:53248
	v_max3_f32 v0, v130, v131, v132
	v_max3_f32 v187, v133, v134, v135
	v_max3_f32 v188, v136, v137, v138
	v_max3_f32 v189, v139, v140, v141
	s_waitcnt lgkmcnt(2)
	v_mfma_f32_32x32x16_bf16 v[98:113], v[182:185], v[248:251], v[98:113]
	ds_read_b64_tr_b16 v[248:249], v252 offset:49408
	ds_read_b64_tr_b16 v[250:251], v252 offset:53504
	v_max3_f32 v0, v0, v142, v143
	v_max3_f32 v187, v187, v144, v145
	v_max3_f32 v0, v0, v187, v188
	v_max_f32_e32 v0, v0, v189
	v_mov_b32_e32 v187, v0
	s_nop 1
	v_permlane32_swap_b32_e32 v0, v187
	v_max_f32_e32 v0, v0, v187
	v_add_f32_e32 v187, 0x41000000, v186
	v_cmp_gt_f32_e32 vcc, v0, v187
	s_cmp_eq_u64 vcc, 0
	v_max_f32_e32 v0, v186, v0
	s_cselect_b64 s[0:1], -1, 0
	v_cndmask_b32_e64 v0, v0, v186, s[0:1]
	v_sub_f32_e32 v247, v186, v0
	v_add_u32_e32 v254, s3, v229
	ds_read_b64_tr_b16 v[186:187], v254 offset:49152
	ds_read_b64_tr_b16 v[188:189], v254 offset:53248
	v_exp_f32_e32 v247, v247
	v_sub_f32_e32 v130, v130, v0
	v_exp_f32_e32 v1, v130
	v_sub_f32_e32 v131, v131, v0
	v_exp_f32_e32 v131, v131
	v_add_f32_e32 v130, 0, v1
	s_waitcnt lgkmcnt(0)
	v_mfma_f32_32x32x16_bf16 v[82:97], v[182:185], v[186:189], v[82:97]
	ds_read_b64_tr_b16 v[186:187], v253 offset:49408
	ds_read_b64_tr_b16 v[188:189], v253 offset:53504
	v_sub_f32_e32 v132, v132, v0
	v_exp_f32_e32 v132, v132
	v_add_f32_e32 v130, v131, v130
	s_waitcnt lgkmcnt(4)
	v_mfma_f32_32x32x16_bf16 v[66:81], v[182:185], v[190:193], v[66:81]
	ds_read_b64_tr_b16 v[190:191], v254 offset:49408
	ds_read_b64_tr_b16 v[192:193], v254 offset:53504
	v_sub_f32_e32 v133, v133, v0
	v_exp_f32_e32 v133, v133
	v_add_f32_e32 v130, v132, v130
	s_cmp_le_u32 s47, s44
	s_cbranch_scc0 .Lmy_a_nov1
	s_mov_b32 m0, s54
	s_nop 0
	global_load_lds_dwordx4 v[206:207], off

.LBB0_1617:
	s_waitcnt lgkmcnt(2)
	v_mfma_f32_32x32x16_bf16 v[114:129], v[182:185], v[190:193], v[114:129]
	v_add_u32_e32 v195, s3, v230
	ds_read_b64_tr_b16 v[190:191], v195 offset:49152
	ds_read_b64_tr_b16 v[192:193], v195 offset:53248
	v_max3_f32 v0, v130, v131, v132
	v_max3_f32 v187, v133, v134, v135
	v_max3_f32 v188, v136, v137, v138
	v_max3_f32 v189, v139, v140, v141
	s_waitcnt lgkmcnt(2)
	v_mfma_f32_32x32x16_bf16 v[98:113], v[182:185], v[248:251], v[98:113]
	ds_read_b64_tr_b16 v[248:249], v252 offset:49408
	ds_read_b64_tr_b16 v[250:251], v252 offset:53504
	v_max3_f32 v0, v0, v142, v143
	v_max3_f32 v187, v187, v144, v145
	v_max3_f32 v0, v0, v187, v188
	v_max_f32_e32 v0, v0, v189
	v_mov_b32_e32 v187, v0
	s_nop 1
	v_permlane32_swap_b32_e32 v0, v187
	v_max_f32_e32 v0, v0, v187
	v_add_f32_e32 v187, 0x41000000, v186
	v_cmp_gt_f32_e32 vcc, v0, v187
	s_cmp_eq_u64 vcc, 0
	v_max_f32_e32 v0, v186, v0
	s_cselect_b64 s[0:1], -1, 0
	v_cndmask_b32_e64 v0, v0, v186, s[0:1]
	v_sub_f32_e32 v247, v186, v0
	v_add_u32_e32 v254, s3, v229
	ds_read_b64_tr_b16 v[186:187], v254 offset:49152
	ds_read_b64_tr_b16 v[188:189], v254 offset:53248
	v_exp_f32_e32 v247, v247
	v_sub_f32_e32 v130, v130, v0
	v_exp_f32_e32 v1, v130
	v_sub_f32_e32 v131, v131, v0
	v_exp_f32_e32 v131, v131
	v_add_f32_e32 v130, 0, v1
	s_waitcnt lgkmcnt(0)
	v_mfma_f32_32x32x16_bf16 v[82:97], v[182:185], v[186:189], v[82:97]
	ds_read_b64_tr_b16 v[186:187], v253 offset:49408
	ds_read_b64_tr_b16 v[188:189], v253 offset:53504
	v_sub_f32_e32 v132, v132, v0
	v_exp_f32_e32 v132, v132
	v_add_f32_e32 v130, v131, v130
	s_waitcnt lgkmcnt(4)
	v_mfma_f32_32x32x16_bf16 v[66:81], v[182:185], v[190:193], v[66:81]
	ds_read_b64_tr_b16 v[190:191], v254 offset:49408
	ds_read_b64_tr_b16 v[192:193], v254 offset:53504
	v_sub_f32_e32 v133, v133, v0
	v_exp_f32_e32 v133, v133
	v_add_f32_e32 v130, v132, v130
	s_cmp_le_u32 s45, s42
	s_cbranch_scc0 .Lmy_b_nov1
	s_mov_b32 m0, s54
	s_nop 0
	global_load_lds_dwordx4 v[206:207], off
